# attention: static priority for waves 4-7 plus loop-path vmcnt re-derivation of the staging waits
# speedup vs baseline: 1.0062x; 1.0007x over previous
; __device__ __forceinline__ void phase_mixer(const Params& p, LAS unsigned char* lds, int dry, int which) {
;     ...
;         u32x4 kr[6], vr[6], qr[2][2];
;         AttnItem I = attn_decode(it - nssd);
;         attn_load(proj, I, tid, kr, vr, qr);
;         for (; it < nssd + nattn; it += G) {
.Lattn_prio_skip:
	s_waitcnt vmcnt(0)
	s_branch .LBB0_332
